# strategy 4 mirrored: one static s_setprio 1 for waves 0-3 set once before the step loop
# speedup vs baseline: 1.0119x; 1.0119x over previous
; __global__ void __launch_bounds__(NTHR, 2) trunk_fwd(Args args) {
;     ...
;     grid.sync();
;     constexpr int NREP = (REPMASK || REPSYNC) ? 2 : 1;
;     for (int it_ = 0; it_ < 32 * NREP; ++it_) {
.LBB0_861:
	v_readfirstlane_b32 s0, v230
	s_nop 3
	s_cmpk_ge_u32 s0, 0x100
	s_cbranch_scc1 .Lprio_done
	s_setprio 1
